# merged epilogue: touch the later groups' gate lines right after the first group's loads
# baseline (speedup 1.0000x reference)
.LBB0_285:
	s_lshl_b32 s6, s6, 10
	s_ashr_i32 s7, s6, 31
	s_lshl_b64 s[14:15], s[6:7], 2
	s_add_u32 s14, s60, s14
	s_addc_u32 s15, s61, s15
	s_lshl_b64 s[6:7], s[6:7], 1
	v_readlane_b32 s18, v255, 24
	v_readlane_b32 s19, v255, 25
	s_add_u32 s6, s18, s6
	s_addc_u32 s7, s19, s7
	v_lshl_add_u64 v[202:203], v[176:177], 1, s[6:7]
	s_movk_i32 s2, 0x1800
	v_mad_i64_i32 v[164:165], s[6:7], v98, s2, v[202:203]
	v_mov_b64_e32 v[230:231], v[164:165]
	global_load_dwordx4 v[208:211], v[164:165], off
	global_load_dwordx4 v[212:215], v[164:165], off offset:2048
	v_lshl_add_u64 v[132:133], v[176:177], 2, s[14:15]
	v_lshl_add_u64 v[132:133], v[174:175], 2, v[132:133]
	s_mov_b64 s[6:7], 0x1000
	v_lshl_add_u64 v[136:137], v[132:133], 0, s[6:7]
	s_movk_i32 s6, 0x1000
	v_add_co_u32_e32 v134, vcc, s6, v132
	v_mad_i64_i32 v[166:167], s[6:7], v172, s2, v[202:203]
	s_nop 0
	v_addc_co_u32_e32 v135, vcc, 0, v133, vcc
	flat_load_dwordx4 v[156:159], v[134:135]
	flat_load_dwordx4 v[160:163], v[132:133]
	flat_load_dwordx4 v[148:151], v[136:137] offset:16
	flat_load_dwordx4 v[152:155], v[132:133] offset:16
	flat_load_dwordx4 v[144:147], v[132:133] offset:512
	s_nop 0
	flat_load_dwordx4 v[132:135], v[132:133] offset:528
	s_nop 0
	flat_load_dwordx4 v[140:143], v[136:137] offset:512
	s_nop 0
	flat_load_dwordx4 v[136:139], v[136:137] offset:528
	s_nop 0
	global_load_dwordx4 v[216:219], v[164:165], off offset:256
	global_load_dwordx4 v[220:223], v[164:165], off offset:2304
	global_load_dwordx4 v[176:179], v[166:167], off
	global_load_dwordx4 v[168:171], v[166:167], off offset:256
	global_load_dwordx4 v[172:175], v[166:167], off offset:2048
	s_nop 0
	global_load_dwordx4 v[164:167], v[166:167], off offset:2304
	s_mov_b32 s98, 0x18000
	s_mov_b32 s99, 0
	v_lshl_add_u64 v[230:231], v[230:231], 0, s[98:99]
	v_lshl_add_u64 v[230:231], v[230:231], 0, s[98:99]
	global_load_dword v228, v[230:231], off
	global_load_dword v228, v[230:231], off offset:2048
	global_load_dword v228, v[230:231], off offset:256
	global_load_dword v228, v[230:231], off offset:2304
	v_lshl_add_u64 v[230:231], v[230:231], 0, s[98:99]
	global_load_dword v228, v[230:231], off
	global_load_dword v228, v[230:231], off offset:2048
	global_load_dword v228, v[230:231], off offset:256
	global_load_dword v228, v[230:231], off offset:2304
	s_mov_b32 s98, 0x78000
	v_lshl_add_u64 v[230:231], v[230:231], 0, s[98:99]
	global_load_dword v228, v[230:231], off
	global_load_dword v228, v[230:231], off offset:2048
	global_load_dword v228, v[230:231], off offset:256
	global_load_dword v228, v[230:231], off offset:2304
	s_mov_b32 s98, 0x18000
	v_lshl_add_u64 v[230:231], v[230:231], 0, s[98:99]
	global_load_dword v228, v[230:231], off
	global_load_dword v228, v[230:231], off offset:2048
	global_load_dword v228, v[230:231], off offset:256
	global_load_dword v228, v[230:231], off offset:2304
	v_lshl_add_u64 v[230:231], v[230:231], 0, s[98:99]
	global_load_dword v228, v[230:231], off
	global_load_dword v228, v[230:231], off offset:2048
	global_load_dword v228, v[230:231], off offset:256
	global_load_dword v228, v[230:231], off offset:2304
	v_lshl_add_u64 v[230:231], v[230:231], 0, s[98:99]
	global_load_dword v228, v[230:231], off
	global_load_dword v228, v[230:231], off offset:2048
	global_load_dword v228, v[230:231], off offset:256
	global_load_dword v228, v[230:231], off offset:2304
	s_waitcnt vmcnt(0)
	v_lshlrev_b32_e32 v96, 16, v208
	v_and_b32_e32 v99, 0xffff0000, v208
	v_lshlrev_b32_e32 v193, 16, v209
	v_and_b32_e32 v201, 0xffff0000, v209
	v_lshlrev_b32_e32 v194, 16, v210
	v_and_b32_e32 v195, 0xffff0000, v210
	v_lshlrev_b32_e32 v196, 16, v211
	v_lshlrev_b32_e32 v197, 16, v212
	v_and_b32_e32 v208, 0xffff0000, v212
	v_lshlrev_b32_e32 v209, 16, v213
	v_lshlrev_b32_e32 v210, 16, v214
	v_lshlrev_b32_e32 v212, 16, v215
	s_waitcnt lgkmcnt(0)
	v_add_f32_e32 v96, v160, v96
	v_add_f32_e32 v210, v148, v210
	v_add_f32_e32 v194, v152, v194
	v_add_f32_e32 v208, v157, v208
	v_add_f32_e32 v209, v158, v209
	v_add_f32_e32 v212, v150, v212
	v_add_f32_e32 v196, v154, v196
	v_mul_f32_e32 v96, 0xbfb8aa3b, v96
	v_and_b32_e32 v225, 0xffff0000, v213
	v_and_b32_e32 v227, 0xffff0000, v215
	v_add_f32_e32 v195, v153, v195
	v_mul_f32_e32 v210, 0xbfb8aa3b, v210
	v_mul_f32_e32 v213, 0xbfb8aa3b, v194
	v_mul_f32_e32 v208, 0xbfb8aa3b, v208
	v_mul_f32_e32 v209, 0xbfb8aa3b, v209
	v_mul_f32_e32 v215, 0xbfb8aa3b, v212
	v_mul_f32_e32 v212, 0xbfb8aa3b, v196
	v_exp_f32_e32 v96, v96
	v_and_b32_e32 v207, 0xffff0000, v211
	v_and_b32_e32 v211, 0xffff0000, v214
	v_mul_f32_e32 v214, 0xbfb8aa3b, v195
	v_exp_f32_e32 v196, v210
	v_exp_f32_e32 v210, v213
	v_exp_f32_e32 v195, v208
	v_exp_f32_e32 v208, v209
	v_exp_f32_e32 v209, v212
	v_add_f32_e32 v96, 1.0, v96
	v_add_f32_e32 v212, 1.0, v210
	v_rcp_f32_e32 v210, v96
	v_add_f32_e32 v96, 1.0, v209
	v_rcp_f32_e32 v226, v96
	v_add_f32_e32 v96, v163, v201
	v_mul_f32_e32 v96, 0xbfb8aa3b, v96
	v_exp_f32_e32 v96, v96
	v_add_f32_e32 v99, v161, v99
	v_add_f32_e32 v197, v156, v197
	v_add_f32_e32 v211, v149, v211
	v_mul_f32_e32 v99, 0xbfb8aa3b, v99
	v_mul_f32_e32 v197, 0xbfb8aa3b, v197
	v_mul_f32_e32 v211, 0xbfb8aa3b, v211
	v_exp_f32_e32 v99, v99
	v_add_f32_e32 v96, 1.0, v96
	v_exp_f32_e32 v194, v197
	v_exp_f32_e32 v197, v211
	v_exp_f32_e32 v211, v214
	v_exp_f32_e32 v224, v215
	v_rcp_f32_e32 v215, v96
	v_add_f32_e32 v96, v155, v207
	v_mul_f32_e32 v96, 0xbfb8aa3b, v96
	v_exp_f32_e32 v96, v96
	v_add_f32_e32 v99, 1.0, v99
	v_add_f32_e32 v213, 1.0, v211
	v_rcp_f32_e32 v211, v99
	v_add_f32_e32 v99, v159, v225
	v_mul_f32_e32 v99, 0xbfb8aa3b, v99
	v_exp_f32_e32 v209, v99
	v_add_f32_e32 v99, v151, v227
	v_add_f32_e32 v96, 1.0, v96
	v_mul_f32_e32 v99, 0xbfb8aa3b, v99
	v_rcp_f32_e32 v227, v96
	v_lshlrev_b32_e32 v96, 16, v216
	v_exp_f32_e32 v225, v99
	v_add_f32_e32 v96, v144, v96
	v_mul_f32_e32 v96, 0xbfb8aa3b, v96
	v_rcp_f32_e32 v212, v212
	v_rcp_f32_e32 v213, v213
	v_pk_add_f32 v[194:195], v[194:195], 1.0 op_sel_hi:[1,0]
	v_exp_f32_e32 v96, v96
	v_pk_mul_f32 v[194:195], v[194:195], v[210:211]
	v_pk_add_f32 v[196:197], v[196:197], 1.0 op_sel_hi:[1,0]
	v_pk_mul_f32 v[128:129], v[128:129], v[194:195]
	v_pk_add_f32 v[194:195], v[224:225], 1.0 op_sel_hi:[1,0]
	v_pk_mul_f32 v[196:197], v[196:197], v[212:213]
	v_pk_mul_f32 v[194:195], v[194:195], v[226:227]
	v_add_f32_e32 v96, 1.0, v96
	v_pk_mul_f32 v[126:127], v[126:127], v[194:195]
	v_lshlrev_b32_e32 v195, 16, v218
	v_pk_mul_f32 v[124:125], v[124:125], v[196:197]
	v_rcp_f32_e32 v196, v96
	v_add_f32_e32 v96, v132, v195
	v_mul_f32_e32 v96, 0xbfb8aa3b, v96
	v_exp_f32_e32 v96, v96
	v_and_b32_e32 v99, 0xffff0000, v216
	v_add_f32_e32 v193, v162, v193
	v_and_b32_e32 v207, 0xffff0000, v218
	v_add_f32_e32 v96, 1.0, v96
	v_rcp_f32_e32 v210, v96
	v_add_f32_e32 v96, v145, v99
	v_mul_f32_e32 v96, 0xbfb8aa3b, v96
	v_exp_f32_e32 v96, v96
	v_and_b32_e32 v197, 0xffff0000, v220
	v_mul_f32_e32 v193, 0xbfb8aa3b, v193
	v_add_f32_e32 v99, v141, v197
	v_add_f32_e32 v96, 1.0, v96
	v_rcp_f32_e32 v197, v96
	v_add_f32_e32 v96, v133, v207
	v_exp_f32_e32 v193, v193
	v_mul_f32_e32 v96, 0xbfb8aa3b, v96
	v_exp_f32_e32 v96, v96
	v_pk_add_f32 v[208:209], v[208:209], 1.0 op_sel_hi:[1,0]
	v_add_f32_e32 v193, 1.0, v193
	v_rcp_f32_e32 v214, v193
	v_lshlrev_b32_e32 v193, 16, v217
	v_add_f32_e32 v96, 1.0, v96
	v_rcp_f32_e32 v211, v96
	v_add_f32_e32 v96, v146, v193
	v_mul_f32_e32 v96, 0xbfb8aa3b, v96
	v_exp_f32_e32 v96, v96
	v_lshlrev_b32_e32 v213, 16, v219
	v_pk_mul_f32 v[208:209], v[208:209], v[214:215]
	v_and_b32_e32 v201, 0xffff0000, v217
	v_add_f32_e32 v96, 1.0, v96
	v_rcp_f32_e32 v214, v96
	v_add_f32_e32 v96, v134, v213
	v_mul_f32_e32 v96, 0xbfb8aa3b, v96
	v_exp_f32_e32 v96, v96
	v_pk_mul_f32 v[130:131], v[130:131], v[208:209]
	v_lshlrev_b32_e32 v208, 16, v222
	v_add_f32_e32 v195, v136, v208
	v_add_f32_e32 v96, 1.0, v96
	v_and_b32_e32 v209, 0xffff0000, v222
	v_mul_f32_e32 v195, 0xbfb8aa3b, v195
	v_mul_f32_e32 v99, 0xbfb8aa3b, v99
	v_rcp_f32_e32 v218, v96
	v_add_f32_e32 v96, v147, v201
	v_exp_f32_e32 v208, v195
	v_exp_f32_e32 v195, v99
	v_add_f32_e32 v99, v137, v209
	v_mul_f32_e32 v96, 0xbfb8aa3b, v96
	v_lshlrev_b32_e32 v212, 16, v221
	v_mul_f32_e32 v99, 0xbfb8aa3b, v99
	v_exp_f32_e32 v96, v96
	v_exp_f32_e32 v209, v99
	v_add_f32_e32 v99, v142, v212
	v_lshlrev_b32_e32 v216, 16, v223
	v_mul_f32_e32 v99, 0xbfb8aa3b, v99
	v_exp_f32_e32 v212, v99
	v_add_f32_e32 v99, v138, v216
	v_and_b32_e32 v217, 0xffff0000, v219
	v_and_b32_e32 v215, 0xffff0000, v221
	v_mul_f32_e32 v99, 0xbfb8aa3b, v99
	v_add_f32_e32 v96, 1.0, v96
	v_exp_f32_e32 v216, v99
	v_add_f32_e32 v99, v143, v215
	v_rcp_f32_e32 v215, v96
	v_add_f32_e32 v96, v135, v217
	v_mul_f32_e32 v96, 0xbfb8aa3b, v96
	v_exp_f32_e32 v96, v96
	v_lshlrev_b32_e32 v194, 16, v220
	v_add_f32_e32 v194, v140, v194
	v_and_b32_e32 v219, 0xffff0000, v223
	v_mul_f32_e32 v194, 0xbfb8aa3b, v194
	v_mul_f32_e32 v99, 0xbfb8aa3b, v99
	v_add_f32_e32 v96, 1.0, v96
	v_exp_f32_e32 v194, v194
	v_exp_f32_e32 v213, v99
	v_add_f32_e32 v99, v139, v219
	v_rcp_f32_e32 v219, v96
	v_lshlrev_b32_e32 v96, 16, v176
	v_mul_f32_e32 v99, 0xbfb8aa3b, v99
	v_add_f32_e32 v96, v160, v96
	v_exp_f32_e32 v217, v99
	v_mul_f32_e32 v96, 0xbfb8aa3b, v96
	v_exp_f32_e32 v96, v96
	v_pk_add_f32 v[212:213], v[212:213], 1.0 op_sel_hi:[1,0]
	v_pk_add_f32 v[194:195], v[194:195], 1.0 op_sel_hi:[1,0]
	v_and_b32_e32 v99, 0xffff0000, v176
	v_pk_mul_f32 v[194:195], v[194:195], v[196:197]
	v_pk_mul_f32 v[196:197], v[212:213], v[214:215]
	v_pk_mul_f32 v[92:93], v[92:93], v[194:195]
	v_pk_mul_f32 v[94:95], v[94:95], v[196:197]
	v_pk_add_f32 v[194:195], v[216:217], 1.0 op_sel_hi:[1,0]
	v_pk_add_f32 v[196:197], v[208:209], 1.0 op_sel_hi:[1,0]
	v_pk_mul_f32 v[194:195], v[194:195], v[218:219]
	v_pk_mul_f32 v[196:197], v[196:197], v[210:211]
	v_lshlrev_b32_e32 v176, 16, v178
	v_add_f32_e32 v96, 1.0, v96
	v_pk_mul_f32 v[90:91], v[90:91], v[194:195]
	v_pk_mul_f32 v[88:89], v[88:89], v[196:197]
	v_lshlrev_b32_e32 v194, 16, v173
	v_and_b32_e32 v207, 0xffff0000, v173
	v_lshlrev_b32_e32 v173, 16, v174
	v_and_b32_e32 v196, 0xffff0000, v174
	v_rcp_f32_e32 v174, v96
	v_add_f32_e32 v96, v152, v176
	v_mul_f32_e32 v96, 0xbfb8aa3b, v96
	v_exp_f32_e32 v96, v96
	v_lshlrev_b32_e32 v193, 16, v177
	v_and_b32_e32 v195, 0xffff0000, v177
	v_and_b32_e32 v177, 0xffff0000, v178
	v_lshlrev_b32_e32 v178, 16, v172
	v_add_f32_e32 v96, 1.0, v96
	v_lshlrev_b32_e32 v197, 16, v179
	v_and_b32_e32 v201, 0xffff0000, v179
	v_and_b32_e32 v179, 0xffff0000, v172
	v_add_f32_e32 v172, v156, v178
	v_rcp_f32_e32 v178, v96
	v_add_f32_e32 v96, v161, v99
	v_mul_f32_e32 v96, 0xbfb8aa3b, v96
	v_exp_f32_e32 v96, v96
	v_lshlrev_b32_e32 v208, 16, v175
	v_and_b32_e32 v209, 0xffff0000, v175
	v_add_f32_e32 v99, v157, v179
	v_add_f32_e32 v96, 1.0, v96
	v_rcp_f32_e32 v175, v96
	v_add_f32_e32 v96, v153, v177
	v_mul_f32_e32 v96, 0xbfb8aa3b, v96
	v_exp_f32_e32 v96, v96
	v_add_f32_e32 v173, v148, v173
	v_mul_f32_e32 v173, 0xbfb8aa3b, v173
	v_mul_f32_e32 v99, 0xbfb8aa3b, v99
	v_add_f32_e32 v96, 1.0, v96
	v_rcp_f32_e32 v179, v96
	v_add_f32_e32 v96, v162, v193
	v_mul_f32_e32 v96, 0xbfb8aa3b, v96
	v_exp_f32_e32 v96, v96
	v_exp_f32_e32 v176, v173
	v_exp_f32_e32 v173, v99
	v_add_f32_e32 v99, v149, v196
	v_add_f32_e32 v96, 1.0, v96
	v_rcp_f32_e32 v196, v96
	v_add_f32_e32 v96, v154, v197
	v_mul_f32_e32 v96, 0xbfb8aa3b, v96
	v_exp_f32_e32 v96, v96
	v_mul_f32_e32 v99, 0xbfb8aa3b, v99
	v_exp_f32_e32 v177, v99
	v_add_f32_e32 v99, v158, v194
	v_add_f32_e32 v96, 1.0, v96
	v_rcp_f32_e32 v210, v96
	v_add_f32_e32 v96, v163, v195
	v_mul_f32_e32 v96, 0xbfb8aa3b, v96
	v_exp_f32_e32 v96, v96
	v_mul_f32_e32 v99, 0xbfb8aa3b, v99
	v_exp_f32_e32 v194, v99
	v_add_f32_e32 v99, v150, v208
	v_add_f32_e32 v96, 1.0, v96
	v_mul_f32_e32 v99, 0xbfb8aa3b, v99
	v_rcp_f32_e32 v197, v96
	v_add_f32_e32 v96, v155, v201
	v_exp_f32_e32 v208, v99
	v_add_f32_e32 v99, v159, v207
	v_mul_f32_e32 v96, 0xbfb8aa3b, v96
	v_mul_f32_e32 v172, 0xbfb8aa3b, v172
	v_mul_f32_e32 v99, 0xbfb8aa3b, v99
	v_exp_f32_e32 v96, v96
	v_exp_f32_e32 v172, v172
	v_exp_f32_e32 v195, v99
	v_add_f32_e32 v99, v151, v209
	v_mul_f32_e32 v99, 0xbfb8aa3b, v99
	v_exp_f32_e32 v209, v99
	v_add_f32_e32 v96, 1.0, v96
	v_rcp_f32_e32 v211, v96
	v_pk_add_f32 v[194:195], v[194:195], 1.0 op_sel_hi:[1,0]
	v_pk_add_f32 v[172:173], v[172:173], 1.0 op_sel_hi:[1,0]
	v_and_b32_e32 v193, 0xffff0000, v165
	v_pk_mul_f32 v[172:173], v[172:173], v[174:175]
	v_pk_mul_f32 v[174:175], v[194:195], v[196:197]
	v_pk_mul_f32 v[120:121], v[120:121], v[172:173]
	v_pk_mul_f32 v[122:123], v[122:123], v[174:175]
	v_pk_add_f32 v[174:175], v[176:177], 1.0 op_sel_hi:[1,0]
	v_pk_add_f32 v[172:173], v[208:209], 1.0 op_sel_hi:[1,0]
	v_pk_mul_f32 v[174:175], v[174:175], v[178:179]
	v_lshlrev_b32_e32 v176, 16, v165
	v_lshlrev_b32_e32 v165, 16, v166
	v_and_b32_e32 v178, 0xffff0000, v166
	v_lshlrev_b32_e32 v194, 16, v167
	v_and_b32_e32 v195, 0xffff0000, v167
	v_mad_i64_i32 v[166:167], s[6:7], v200, s2, v[202:203]
	v_pk_mul_f32 v[172:173], v[172:173], v[210:211]
	global_load_dwordx4 v[208:211], v[166:167], off
	global_load_dwordx4 v[212:215], v[166:167], off offset:2048
	v_lshlrev_b32_e32 v96, 16, v168
	v_add_f32_e32 v96, v144, v96
	v_mul_f32_e32 v96, 0xbfb8aa3b, v96
	v_exp_f32_e32 v96, v96
	v_pk_mul_f32 v[116:117], v[116:117], v[174:175]
	v_and_b32_e32 v99, 0xffff0000, v168
	v_lshlrev_b32_e32 v174, 16, v169
	v_and_b32_e32 v175, 0xffff0000, v169
	v_lshlrev_b32_e32 v169, 16, v170
	v_lshlrev_b32_e32 v168, 16, v164
	v_add_f32_e32 v96, 1.0, v96
	v_lshlrev_b32_e32 v177, 16, v171
	v_and_b32_e32 v179, 0xffff0000, v171
	v_and_b32_e32 v171, 0xffff0000, v164
	v_add_f32_e32 v164, v140, v168
	v_rcp_f32_e32 v168, v96
	v_add_f32_e32 v96, v136, v165
	v_add_f32_e32 v165, v132, v169
	v_mul_f32_e32 v165, 0xbfb8aa3b, v165
	v_exp_f32_e32 v165, v165
	v_mul_f32_e32 v96, 0xbfb8aa3b, v96
	v_pk_mul_f32 v[118:119], v[118:119], v[172:173]
	v_and_b32_e32 v173, 0xffff0000, v170
	v_exp_f32_e32 v170, v96
	v_add_f32_e32 v96, 1.0, v165
	v_rcp_f32_e32 v172, v96
	v_add_f32_e32 v96, v145, v99
	v_mul_f32_e32 v96, 0xbfb8aa3b, v96
	v_exp_f32_e32 v96, v96
	v_add_f32_e32 v99, v141, v171
	v_mul_f32_e32 v99, 0xbfb8aa3b, v99
	v_exp_f32_e32 v165, v99
	v_add_f32_e32 v96, 1.0, v96
	v_rcp_f32_e32 v169, v96
	v_add_f32_e32 v96, v133, v173
	v_mul_f32_e32 v96, 0xbfb8aa3b, v96
	v_exp_f32_e32 v96, v96
	v_add_f32_e32 v99, v137, v178
	v_mul_f32_e32 v99, 0xbfb8aa3b, v99
	global_load_dwordx4 v[216:219], v[166:167], off offset:256
	global_load_dwordx4 v[220:223], v[166:167], off offset:2304
	v_add_f32_e32 v96, 1.0, v96
	v_rcp_f32_e32 v173, v96
	v_add_f32_e32 v96, v146, v174
	v_mul_f32_e32 v96, 0xbfb8aa3b, v96
	v_exp_f32_e32 v96, v96
	v_exp_f32_e32 v171, v99
	v_add_f32_e32 v99, v142, v176
	v_mul_f32_e32 v99, 0xbfb8aa3b, v99
	v_add_f32_e32 v96, 1.0, v96
	v_rcp_f32_e32 v176, v96
	v_add_f32_e32 v96, v134, v177
	v_mul_f32_e32 v96, 0xbfb8aa3b, v96
	v_exp_f32_e32 v96, v96
	v_exp_f32_e32 v174, v99
	v_add_f32_e32 v99, v138, v194
	v_mul_f32_e32 v99, 0xbfb8aa3b, v99
	v_add_f32_e32 v96, 1.0, v96
	v_rcp_f32_e32 v194, v96
	v_add_f32_e32 v96, v147, v175
	v_mul_f32_e32 v96, 0xbfb8aa3b, v96
	v_exp_f32_e32 v96, v96
	v_exp_f32_e32 v178, v99
	v_add_f32_e32 v99, v143, v193
	v_mul_f32_e32 v99, 0xbfb8aa3b, v99
	v_add_f32_e32 v96, 1.0, v96
	v_rcp_f32_e32 v177, v96
	v_add_f32_e32 v96, v135, v179
	v_mul_f32_e32 v96, 0xbfb8aa3b, v96
	v_exp_f32_e32 v96, v96
	v_mul_f32_e32 v164, 0xbfb8aa3b, v164
	v_exp_f32_e32 v175, v99
	v_add_f32_e32 v99, v139, v195
	v_add_f32_e32 v96, 1.0, v96
	v_rcp_f32_e32 v195, v96
	v_exp_f32_e32 v164, v164
	v_mul_f32_e32 v99, 0xbfb8aa3b, v99
	v_exp_f32_e32 v179, v99
	v_pk_add_f32 v[174:175], v[174:175], 1.0 op_sel_hi:[1,0]
	s_waitcnt vmcnt(3)
	v_lshlrev_b32_e32 v96, 16, v208
	v_add_f32_e32 v96, v160, v96
	v_mul_f32_e32 v96, 0xbfb8aa3b, v96
	v_exp_f32_e32 v96, v96
	v_pk_add_f32 v[164:165], v[164:165], 1.0 op_sel_hi:[1,0]
	v_lshlrev_b32_e32 v193, 16, v210
	v_pk_mul_f32 v[164:165], v[164:165], v[168:169]
	v_add_f32_e32 v96, 1.0, v96
	v_pk_mul_f32 v[84:85], v[84:85], v[164:165]
	v_pk_add_f32 v[164:165], v[178:179], 1.0 op_sel_hi:[1,0]
	v_and_b32_e32 v99, 0xffff0000, v208
	v_pk_mul_f32 v[164:165], v[164:165], v[194:195]
	v_rcp_f32_e32 v194, v96
	v_add_f32_e32 v96, v152, v193
	v_mul_f32_e32 v96, 0xbfb8aa3b, v96
	v_exp_f32_e32 v96, v96
	v_and_b32_e32 v197, 0xffff0000, v210
	s_waitcnt vmcnt(2)
	v_and_b32_e32 v195, 0xffff0000, v212
	v_lshlrev_b32_e32 v196, 16, v214
	v_add_f32_e32 v96, 1.0, v96
	v_rcp_f32_e32 v200, v96
	v_add_f32_e32 v96, v161, v99
	v_mul_f32_e32 v96, 0xbfb8aa3b, v96
	v_exp_f32_e32 v96, v96
	v_add_f32_e32 v99, v157, v195
	v_add_f32_e32 v193, v148, v196
	v_lshlrev_b32_e32 v207, 16, v209
	v_add_f32_e32 v96, 1.0, v96
	v_rcp_f32_e32 v195, v96
	v_add_f32_e32 v96, v153, v197
	v_mul_f32_e32 v96, 0xbfb8aa3b, v96
	v_exp_f32_e32 v96, v96
	v_and_b32_e32 v201, 0xffff0000, v214
	v_mul_f32_e32 v193, 0xbfb8aa3b, v193
	v_mul_f32_e32 v99, 0xbfb8aa3b, v99
	v_add_f32_e32 v96, 1.0, v96
	v_exp_f32_e32 v196, v193
	v_exp_f32_e32 v193, v99
	v_add_f32_e32 v99, v149, v201
	v_rcp_f32_e32 v201, v96
	v_add_f32_e32 v96, v162, v207
	v_mul_f32_e32 v96, 0xbfb8aa3b, v96
	v_exp_f32_e32 v96, v96
	v_pk_mul_f32 v[168:169], v[174:175], v[176:177]
	v_lshlrev_b32_e32 v224, 16, v211
	v_pk_mul_f32 v[86:87], v[86:87], v[168:169]
	v_pk_add_f32 v[168:169], v[170:171], 1.0 op_sel_hi:[1,0]
	v_add_f32_e32 v96, 1.0, v96
	v_pk_mul_f32 v[168:169], v[168:169], v[172:173]
	v_pk_mul_f32 v[82:83], v[82:83], v[164:165]
	v_mad_i64_i32 v[164:165], s[6:7], v192, s2, v[202:203]
	v_rcp_f32_e32 v210, v96
	v_add_f32_e32 v96, v154, v224
	v_pk_mul_f32 v[80:81], v[80:81], v[168:169]
	global_load_dwordx4 v[176:179], v[164:165], off
	global_load_dwordx4 v[168:171], v[164:165], off offset:256
	global_load_dwordx4 v[172:175], v[164:165], off offset:2048
	s_nop 0
	global_load_dwordx4 v[164:167], v[164:165], off offset:2304
	v_mul_f32_e32 v96, 0xbfb8aa3b, v96
	v_exp_f32_e32 v96, v96
	v_and_b32_e32 v209, 0xffff0000, v209
	v_lshlrev_b32_e32 v208, 16, v213
	v_mul_f32_e32 v99, 0xbfb8aa3b, v99
	v_add_f32_e32 v96, 1.0, v96
	v_rcp_f32_e32 v214, v96
	v_add_f32_e32 v96, v163, v209
	v_mul_f32_e32 v96, 0xbfb8aa3b, v96
	v_exp_f32_e32 v96, v96
	v_exp_f32_e32 v197, v99
	v_add_f32_e32 v99, v158, v208
	v_lshlrev_b32_e32 v192, 16, v212
	v_lshlrev_b32_e32 v212, 16, v215
	v_mul_f32_e32 v99, 0xbfb8aa3b, v99
	v_exp_f32_e32 v208, v99
	v_add_f32_e32 v99, v150, v212
	v_and_b32_e32 v225, 0xffff0000, v211
	v_and_b32_e32 v211, 0xffff0000, v213
	v_mul_f32_e32 v99, 0xbfb8aa3b, v99
	v_add_f32_e32 v96, 1.0, v96
	v_exp_f32_e32 v212, v99
	v_add_f32_e32 v99, v159, v211
	v_rcp_f32_e32 v211, v96
	v_add_f32_e32 v96, v155, v225
	v_mul_f32_e32 v96, 0xbfb8aa3b, v96
	v_exp_f32_e32 v96, v96
	v_add_f32_e32 v192, v156, v192
	v_and_b32_e32 v213, 0xffff0000, v215
	v_mul_f32_e32 v192, 0xbfb8aa3b, v192
	v_mul_f32_e32 v99, 0xbfb8aa3b, v99
	v_exp_f32_e32 v192, v192
	v_exp_f32_e32 v209, v99
	v_add_f32_e32 v99, v151, v213
	v_add_f32_e32 v96, 1.0, v96
	v_mul_f32_e32 v99, 0xbfb8aa3b, v99
	v_rcp_f32_e32 v215, v96
	s_waitcnt vmcnt(5)
	v_lshlrev_b32_e32 v96, 16, v216
	v_exp_f32_e32 v213, v99
	v_add_f32_e32 v96, v144, v96
	v_mul_f32_e32 v96, 0xbfb8aa3b, v96
	v_pk_add_f32 v[192:193], v[192:193], 1.0 op_sel_hi:[1,0]
	v_exp_f32_e32 v96, v96
	v_pk_add_f32 v[208:209], v[208:209], 1.0 op_sel_hi:[1,0]
	v_pk_mul_f32 v[192:193], v[192:193], v[194:195]
	v_pk_mul_f32 v[194:195], v[208:209], v[210:211]
	v_pk_mul_f32 v[112:113], v[112:113], v[192:193]
	v_pk_add_f32 v[192:193], v[212:213], 1.0 op_sel_hi:[1,0]
	v_pk_mul_f32 v[114:115], v[114:115], v[194:195]
	v_pk_add_f32 v[194:195], v[196:197], 1.0 op_sel_hi:[1,0]
	v_pk_mul_f32 v[192:193], v[192:193], v[214:215]
	v_pk_mul_f32 v[194:195], v[194:195], v[200:201]
	v_pk_mul_f32 v[110:111], v[110:111], v[192:193]
	v_lshlrev_b32_e32 v193, 16, v218
	v_add_f32_e32 v96, 1.0, v96
	v_pk_mul_f32 v[108:109], v[108:109], v[194:195]
	v_rcp_f32_e32 v194, v96
	v_add_f32_e32 v96, v132, v193
	v_mul_f32_e32 v96, 0xbfb8aa3b, v96
	v_exp_f32_e32 v96, v96
	v_and_b32_e32 v99, 0xffff0000, v216
	v_and_b32_e32 v197, 0xffff0000, v218
	s_waitcnt vmcnt(4)
	v_and_b32_e32 v195, 0xffff0000, v220
	v_add_f32_e32 v96, 1.0, v96
	v_rcp_f32_e32 v200, v96
	v_add_f32_e32 v96, v145, v99
	v_mul_f32_e32 v96, 0xbfb8aa3b, v96
	v_exp_f32_e32 v96, v96
	v_add_f32_e32 v99, v141, v195
	v_lshlrev_b32_e32 v196, 16, v222
	v_add_f32_e32 v193, v136, v196
	v_add_f32_e32 v96, 1.0, v96
	v_rcp_f32_e32 v195, v96
	v_add_f32_e32 v96, v133, v197
	v_mul_f32_e32 v96, 0xbfb8aa3b, v96
	v_exp_f32_e32 v96, v96
	v_lshlrev_b32_e32 v207, 16, v217
	v_and_b32_e32 v201, 0xffff0000, v222
	v_mul_f32_e32 v193, 0xbfb8aa3b, v193
	v_mul_f32_e32 v99, 0xbfb8aa3b, v99
	v_add_f32_e32 v96, 1.0, v96
	v_exp_f32_e32 v196, v193
	v_exp_f32_e32 v193, v99
	v_add_f32_e32 v99, v137, v201
	v_rcp_f32_e32 v201, v96
	v_add_f32_e32 v96, v146, v207
	v_mul_f32_e32 v96, 0xbfb8aa3b, v96
	v_exp_f32_e32 v96, v96
	v_lshlrev_b32_e32 v211, 16, v219
	v_and_b32_e32 v209, 0xffff0000, v217
	v_and_b32_e32 v213, 0xffff0000, v219
	v_add_f32_e32 v96, 1.0, v96
	v_rcp_f32_e32 v210, v96
	v_add_f32_e32 v96, v134, v211
	v_mul_f32_e32 v96, 0xbfb8aa3b, v96
	v_exp_f32_e32 v96, v96
	v_lshlrev_b32_e32 v208, 16, v221
	v_mul_f32_e32 v99, 0xbfb8aa3b, v99
	v_exp_f32_e32 v197, v99
	v_add_f32_e32 v96, 1.0, v96
	v_rcp_f32_e32 v214, v96
	v_add_f32_e32 v96, v147, v209
	v_mul_f32_e32 v96, 0xbfb8aa3b, v96
	v_exp_f32_e32 v96, v96
	v_add_f32_e32 v99, v142, v208
	v_lshlrev_b32_e32 v212, 16, v223
	v_mul_f32_e32 v99, 0xbfb8aa3b, v99
	v_add_f32_e32 v96, 1.0, v96
	v_rcp_f32_e32 v211, v96
	v_add_f32_e32 v96, v135, v213
	v_mul_f32_e32 v96, 0xbfb8aa3b, v96
	v_exp_f32_e32 v96, v96
	v_exp_f32_e32 v208, v99
	v_add_f32_e32 v99, v138, v212
	v_lshlrev_b32_e32 v192, 16, v220
	v_and_b32_e32 v215, 0xffff0000, v221
	v_mul_f32_e32 v99, 0xbfb8aa3b, v99
	v_add_f32_e32 v192, v140, v192
	v_exp_f32_e32 v212, v99
	v_add_f32_e32 v99, v143, v215
	v_mul_f32_e32 v192, 0xbfb8aa3b, v192
	v_mul_f32_e32 v99, 0xbfb8aa3b, v99
	v_add_f32_e32 v96, 1.0, v96
	v_exp_f32_e32 v192, v192
	v_exp_f32_e32 v209, v99
	v_rcp_f32_e32 v215, v96
	s_waitcnt vmcnt(3)
	v_lshlrev_b32_e32 v96, 16, v176
	v_add_f32_e32 v96, v160, v96
	v_mul_f32_e32 v96, 0xbfb8aa3b, v96
	v_exp_f32_e32 v96, v96
	v_and_b32_e32 v216, 0xffff0000, v223
	v_pk_add_f32 v[208:209], v[208:209], 1.0 op_sel_hi:[1,0]
	v_pk_add_f32 v[192:193], v[192:193], 1.0 op_sel_hi:[1,0]
	v_add_f32_e32 v99, v139, v216
	v_pk_mul_f32 v[192:193], v[192:193], v[194:195]
	v_pk_mul_f32 v[194:195], v[208:209], v[210:211]
	v_mul_f32_e32 v99, 0xbfb8aa3b, v99
	v_pk_mul_f32 v[78:79], v[78:79], v[194:195]
	v_pk_add_f32 v[194:195], v[196:197], 1.0 op_sel_hi:[1,0]
	v_exp_f32_e32 v213, v99
	v_pk_mul_f32 v[194:195], v[194:195], v[200:201]
	v_and_b32_e32 v99, 0xffff0000, v176
	v_lshlrev_b32_e32 v176, 16, v178
	v_add_f32_e32 v96, 1.0, v96
	v_pk_mul_f32 v[72:73], v[72:73], v[194:195]
	s_waitcnt vmcnt(1)
	v_lshlrev_b32_e32 v194, 16, v173
	v_and_b32_e32 v201, 0xffff0000, v173
	v_lshlrev_b32_e32 v173, 16, v174
	v_and_b32_e32 v196, 0xffff0000, v174
	v_rcp_f32_e32 v174, v96
	v_add_f32_e32 v96, v152, v176
	v_mul_f32_e32 v96, 0xbfb8aa3b, v96
	v_exp_f32_e32 v96, v96
	v_pk_mul_f32 v[76:77], v[76:77], v[192:193]
	v_pk_add_f32 v[192:193], v[212:213], 1.0 op_sel_hi:[1,0]
	v_lshlrev_b32_e32 v195, 16, v179
	v_pk_mul_f32 v[192:193], v[192:193], v[214:215]
	v_add_f32_e32 v96, 1.0, v96
	v_pk_mul_f32 v[74:75], v[74:75], v[192:193]
	v_lshlrev_b32_e32 v192, 16, v177
	v_and_b32_e32 v193, 0xffff0000, v177
	v_and_b32_e32 v177, 0xffff0000, v178
	v_lshlrev_b32_e32 v178, 16, v172
	v_and_b32_e32 v197, 0xffff0000, v179
	v_and_b32_e32 v179, 0xffff0000, v172
	v_add_f32_e32 v172, v156, v178
	v_rcp_f32_e32 v178, v96
	v_add_f32_e32 v96, v161, v99
	v_mul_f32_e32 v96, 0xbfb8aa3b, v96
	v_exp_f32_e32 v96, v96
	v_lshlrev_b32_e32 v200, 16, v175
	v_and_b32_e32 v207, 0xffff0000, v175
	v_add_f32_e32 v99, v157, v179
	v_add_f32_e32 v96, 1.0, v96
	v_rcp_f32_e32 v175, v96
	v_add_f32_e32 v96, v153, v177
	v_mul_f32_e32 v96, 0xbfb8aa3b, v96
	v_exp_f32_e32 v96, v96
	v_add_f32_e32 v173, v148, v173
	v_mul_f32_e32 v173, 0xbfb8aa3b, v173
	v_mul_f32_e32 v99, 0xbfb8aa3b, v99
	v_add_f32_e32 v96, 1.0, v96
	v_rcp_f32_e32 v179, v96
	v_add_f32_e32 v96, v162, v192
	v_mul_f32_e32 v96, 0xbfb8aa3b, v96
	v_exp_f32_e32 v96, v96
	v_exp_f32_e32 v176, v173
	v_exp_f32_e32 v173, v99
	v_add_f32_e32 v99, v149, v196
	v_mul_f32_e32 v99, 0xbfb8aa3b, v99
	v_add_f32_e32 v96, 1.0, v96
	v_exp_f32_e32 v177, v99
	v_add_f32_e32 v99, v158, v194
	v_rcp_f32_e32 v194, v96
	v_add_f32_e32 v96, v154, v195
	v_mul_f32_e32 v96, 0xbfb8aa3b, v96
	v_exp_f32_e32 v96, v96
	v_mul_f32_e32 v99, 0xbfb8aa3b, v99
	v_exp_f32_e32 v192, v99
	v_add_f32_e32 v99, v150, v200
	v_add_f32_e32 v96, 1.0, v96
	v_rcp_f32_e32 v200, v96
	v_add_f32_e32 v96, v163, v193
	v_mul_f32_e32 v96, 0xbfb8aa3b, v96
	v_exp_f32_e32 v96, v96
	v_mul_f32_e32 v99, 0xbfb8aa3b, v99
	v_exp_f32_e32 v196, v99
	v_add_f32_e32 v99, v159, v201
	v_mul_f32_e32 v172, 0xbfb8aa3b, v172
	v_mul_f32_e32 v99, 0xbfb8aa3b, v99
	v_exp_f32_e32 v172, v172
	v_exp_f32_e32 v193, v99
	v_add_f32_e32 v96, 1.0, v96
	v_rcp_f32_e32 v195, v96
	v_pk_add_f32 v[172:173], v[172:173], 1.0 op_sel_hi:[1,0]
	v_pk_add_f32 v[192:193], v[192:193], 1.0 op_sel_hi:[1,0]
	v_pk_mul_f32 v[172:173], v[172:173], v[174:175]
	v_pk_mul_f32 v[174:175], v[192:193], v[194:195]
	s_waitcnt vmcnt(0)
	v_and_b32_e32 v193, 0xffff0000, v165
	v_pk_mul_f32 v[106:107], v[106:107], v[174:175]
	v_pk_add_f32 v[174:175], v[176:177], 1.0 op_sel_hi:[1,0]
	v_lshlrev_b32_e32 v176, 16, v165
	v_pk_mul_f32 v[174:175], v[174:175], v[178:179]
	v_lshlrev_b32_e32 v165, 16, v166
	v_and_b32_e32 v178, 0xffff0000, v166
	v_add_u32_e32 v166, 0x80, v98
	v_lshlrev_b32_e32 v192, 16, v167
	v_and_b32_e32 v194, 0xffff0000, v167
	v_mad_i64_i32 v[166:167], s[6:7], v166, s2, v[202:203]
	global_load_dwordx4 v[208:211], v[166:167], off
	global_load_dwordx4 v[212:215], v[166:167], off offset:2048
	v_add_f32_e32 v96, v155, v197
	v_mul_f32_e32 v96, 0xbfb8aa3b, v96
	v_exp_f32_e32 v96, v96
	v_add_f32_e32 v99, v151, v207
	v_mul_f32_e32 v99, 0xbfb8aa3b, v99
	v_exp_f32_e32 v197, v99
	v_add_f32_e32 v96, 1.0, v96
	v_rcp_f32_e32 v201, v96
	v_lshlrev_b32_e32 v96, 16, v168
	v_add_f32_e32 v96, v144, v96
	v_mul_f32_e32 v96, 0xbfb8aa3b, v96
	v_exp_f32_e32 v96, v96
	v_pk_mul_f32 v[100:101], v[100:101], v[174:175]
	v_and_b32_e32 v99, 0xffff0000, v168
	v_lshlrev_b32_e32 v174, 16, v169
	v_and_b32_e32 v175, 0xffff0000, v169
	v_lshlrev_b32_e32 v169, 16, v170
	v_lshlrev_b32_e32 v168, 16, v164
	v_add_f32_e32 v96, 1.0, v96
	v_lshlrev_b32_e32 v177, 16, v171
	v_and_b32_e32 v179, 0xffff0000, v171
	v_and_b32_e32 v171, 0xffff0000, v164
	v_add_f32_e32 v164, v140, v168
	v_rcp_f32_e32 v168, v96
	v_add_f32_e32 v96, v136, v165
	v_add_f32_e32 v165, v132, v169
	v_mul_f32_e32 v165, 0xbfb8aa3b, v165
	v_exp_f32_e32 v165, v165
	v_pk_mul_f32 v[104:105], v[104:105], v[172:173]
	v_pk_add_f32 v[172:173], v[196:197], 1.0 op_sel_hi:[1,0]
	v_mul_f32_e32 v96, 0xbfb8aa3b, v96
	v_pk_mul_f32 v[172:173], v[172:173], v[200:201]
	global_load_dwordx4 v[216:219], v[166:167], off offset:256
	global_load_dwordx4 v[220:223], v[166:167], off offset:2304
	v_pk_mul_f32 v[102:103], v[102:103], v[172:173]
	v_and_b32_e32 v173, 0xffff0000, v170
	v_exp_f32_e32 v170, v96
	v_add_f32_e32 v96, 1.0, v165
	v_rcp_f32_e32 v172, v96
	v_add_f32_e32 v96, v145, v99
	v_mul_f32_e32 v96, 0xbfb8aa3b, v96
	v_exp_f32_e32 v96, v96
	v_add_f32_e32 v99, v141, v171
	v_mul_f32_e32 v99, 0xbfb8aa3b, v99
	v_exp_f32_e32 v165, v99
	v_add_f32_e32 v96, 1.0, v96
	v_rcp_f32_e32 v169, v96
	v_add_f32_e32 v96, v133, v173
	v_mul_f32_e32 v96, 0xbfb8aa3b, v96
	v_exp_f32_e32 v96, v96
	v_add_f32_e32 v99, v137, v178
	v_mul_f32_e32 v99, 0xbfb8aa3b, v99
	v_exp_f32_e32 v171, v99
	v_add_f32_e32 v96, 1.0, v96
	v_rcp_f32_e32 v173, v96
	v_add_f32_e32 v96, v146, v174
	v_mul_f32_e32 v96, 0xbfb8aa3b, v96
	v_exp_f32_e32 v96, v96
	v_add_f32_e32 v99, v142, v176
	v_mul_f32_e32 v99, 0xbfb8aa3b, v99
	v_exp_f32_e32 v174, v99
	v_add_f32_e32 v96, 1.0, v96
	v_rcp_f32_e32 v176, v96
	v_add_f32_e32 v96, v134, v177
	v_mul_f32_e32 v96, 0xbfb8aa3b, v96
	v_exp_f32_e32 v96, v96
	v_add_f32_e32 v99, v138, v192
	v_mul_f32_e32 v99, 0xbfb8aa3b, v99
	v_exp_f32_e32 v178, v99
	v_add_f32_e32 v96, 1.0, v96
	v_rcp_f32_e32 v192, v96
	v_add_f32_e32 v96, v147, v175
	v_mul_f32_e32 v96, 0xbfb8aa3b, v96
	v_exp_f32_e32 v96, v96
	v_add_f32_e32 v99, v143, v193
	v_mul_f32_e32 v164, 0xbfb8aa3b, v164
	v_mul_f32_e32 v99, 0xbfb8aa3b, v99
	v_add_f32_e32 v96, 1.0, v96
	v_rcp_f32_e32 v177, v96
	v_add_f32_e32 v96, v135, v179
	v_mul_f32_e32 v96, 0xbfb8aa3b, v96
	v_exp_f32_e32 v96, v96
	v_exp_f32_e32 v164, v164
	v_exp_f32_e32 v175, v99
	v_add_f32_e32 v99, v139, v194
	v_mul_f32_e32 v99, 0xbfb8aa3b, v99
	v_exp_f32_e32 v179, v99
	v_add_f32_e32 v96, 1.0, v96
	v_rcp_f32_e32 v193, v96
	v_pk_add_f32 v[164:165], v[164:165], 1.0 op_sel_hi:[1,0]
	v_add_u32_e32 v96, 0x90, v98
	v_pk_mul_f32 v[164:165], v[164:165], v[168:169]
	s_waitcnt vmcnt(3)
	v_and_b32_e32 v99, 0xffff0000, v208
	v_pk_mul_f32 v[68:69], v[68:69], v[164:165]
	v_pk_add_f32 v[164:165], v[178:179], 1.0 op_sel_hi:[1,0]
	v_and_b32_e32 v197, 0xffff0000, v210
	v_pk_mul_f32 v[164:165], v[164:165], v[192:193]
	v_lshlrev_b32_e32 v193, 16, v210
	v_pk_mul_f32 v[66:67], v[66:67], v[164:165]
	v_mad_i64_i32 v[164:165], s[6:7], v96, s2, v[202:203]
	v_lshlrev_b32_e32 v96, 16, v208
	v_add_f32_e32 v96, v160, v96
	v_mul_f32_e32 v96, 0xbfb8aa3b, v96
	v_exp_f32_e32 v96, v96
	s_waitcnt vmcnt(2)
	v_and_b32_e32 v195, 0xffff0000, v212
	v_lshlrev_b32_e32 v196, 16, v214
	v_lshlrev_b32_e32 v207, 16, v209
	v_add_f32_e32 v96, 1.0, v96
	v_rcp_f32_e32 v194, v96
	v_add_f32_e32 v96, v152, v193
	v_mul_f32_e32 v96, 0xbfb8aa3b, v96
	v_exp_f32_e32 v96, v96
	v_add_f32_e32 v193, v148, v196
	v_and_b32_e32 v201, 0xffff0000, v214
	v_mul_f32_e32 v193, 0xbfb8aa3b, v193
	v_add_f32_e32 v96, 1.0, v96
	v_rcp_f32_e32 v200, v96
	v_add_f32_e32 v96, v161, v99
	v_mul_f32_e32 v96, 0xbfb8aa3b, v96
	v_exp_f32_e32 v96, v96
	v_add_f32_e32 v99, v157, v195
	v_mul_f32_e32 v99, 0xbfb8aa3b, v99
	v_exp_f32_e32 v196, v193
	v_add_f32_e32 v96, 1.0, v96
	v_rcp_f32_e32 v195, v96
	v_add_f32_e32 v96, v153, v197
	v_mul_f32_e32 v96, 0xbfb8aa3b, v96
	v_exp_f32_e32 v96, v96
	v_exp_f32_e32 v193, v99
	v_add_f32_e32 v99, v149, v201
	v_pk_add_f32 v[174:175], v[174:175], 1.0 op_sel_hi:[1,0]
	v_add_f32_e32 v96, 1.0, v96
	v_rcp_f32_e32 v201, v96
	v_add_f32_e32 v96, v162, v207
	v_mul_f32_e32 v96, 0xbfb8aa3b, v96
	v_exp_f32_e32 v96, v96
	v_pk_mul_f32 v[168:169], v[174:175], v[176:177]
	v_lshlrev_b32_e32 v224, 16, v211
	v_pk_mul_f32 v[70:71], v[70:71], v[168:169]
	v_pk_add_f32 v[168:169], v[170:171], 1.0 op_sel_hi:[1,0]
	v_add_f32_e32 v96, 1.0, v96
	v_pk_mul_f32 v[168:169], v[168:169], v[172:173]
	v_rcp_f32_e32 v210, v96
	v_add_f32_e32 v96, v154, v224
	v_pk_mul_f32 v[64:65], v[64:65], v[168:169]
	global_load_dwordx4 v[176:179], v[164:165], off
	global_load_dwordx4 v[168:171], v[164:165], off offset:256
	global_load_dwordx4 v[172:175], v[164:165], off offset:2048
	s_nop 0
	global_load_dwordx4 v[164:167], v[164:165], off offset:2304
	v_mul_f32_e32 v96, 0xbfb8aa3b, v96
	v_exp_f32_e32 v96, v96
	v_and_b32_e32 v209, 0xffff0000, v209
	v_lshlrev_b32_e32 v208, 16, v213
	v_mul_f32_e32 v99, 0xbfb8aa3b, v99
	v_add_f32_e32 v96, 1.0, v96
	v_rcp_f32_e32 v214, v96
	v_add_f32_e32 v96, v163, v209
	v_mul_f32_e32 v96, 0xbfb8aa3b, v96
	v_exp_f32_e32 v96, v96
	v_exp_f32_e32 v197, v99
	v_add_f32_e32 v99, v158, v208
	v_lshlrev_b32_e32 v192, 16, v212
	v_lshlrev_b32_e32 v212, 16, v215
	v_mul_f32_e32 v99, 0xbfb8aa3b, v99
	v_exp_f32_e32 v208, v99
	v_add_f32_e32 v99, v150, v212
	v_and_b32_e32 v225, 0xffff0000, v211
	v_and_b32_e32 v211, 0xffff0000, v213
	v_mul_f32_e32 v99, 0xbfb8aa3b, v99
	v_add_f32_e32 v96, 1.0, v96
	v_exp_f32_e32 v212, v99
	v_add_f32_e32 v99, v159, v211
	v_rcp_f32_e32 v211, v96
	v_add_f32_e32 v96, v155, v225
	v_mul_f32_e32 v96, 0xbfb8aa3b, v96
	v_exp_f32_e32 v96, v96
	v_add_f32_e32 v192, v156, v192
	v_and_b32_e32 v213, 0xffff0000, v215
	v_mul_f32_e32 v192, 0xbfb8aa3b, v192
	v_mul_f32_e32 v99, 0xbfb8aa3b, v99
	v_exp_f32_e32 v192, v192
	v_exp_f32_e32 v209, v99
	v_add_f32_e32 v99, v151, v213
	v_add_f32_e32 v96, 1.0, v96
	v_mul_f32_e32 v99, 0xbfb8aa3b, v99
	v_rcp_f32_e32 v215, v96
	s_waitcnt vmcnt(5)
	v_lshlrev_b32_e32 v96, 16, v216
	v_exp_f32_e32 v213, v99
	v_add_f32_e32 v96, v144, v96
	v_mul_f32_e32 v96, 0xbfb8aa3b, v96
	v_pk_add_f32 v[192:193], v[192:193], 1.0 op_sel_hi:[1,0]
	v_exp_f32_e32 v96, v96
	v_pk_add_f32 v[208:209], v[208:209], 1.0 op_sel_hi:[1,0]
	v_pk_mul_f32 v[192:193], v[192:193], v[194:195]
	v_pk_mul_f32 v[194:195], v[208:209], v[210:211]
	v_pk_mul_f32 v[60:61], v[60:61], v[192:193]
	v_pk_add_f32 v[192:193], v[212:213], 1.0 op_sel_hi:[1,0]
	v_pk_mul_f32 v[62:63], v[62:63], v[194:195]
	v_pk_add_f32 v[194:195], v[196:197], 1.0 op_sel_hi:[1,0]
	v_pk_mul_f32 v[192:193], v[192:193], v[214:215]
	v_pk_mul_f32 v[194:195], v[194:195], v[200:201]
	v_pk_mul_f32 v[58:59], v[58:59], v[192:193]
	v_lshlrev_b32_e32 v193, 16, v218
	v_add_f32_e32 v96, 1.0, v96
	v_pk_mul_f32 v[56:57], v[56:57], v[194:195]
	v_rcp_f32_e32 v194, v96
	v_add_f32_e32 v96, v132, v193
	v_mul_f32_e32 v96, 0xbfb8aa3b, v96
	v_exp_f32_e32 v96, v96
	v_and_b32_e32 v99, 0xffff0000, v216
	v_and_b32_e32 v197, 0xffff0000, v218
	s_waitcnt vmcnt(4)
	v_and_b32_e32 v195, 0xffff0000, v220
	v_add_f32_e32 v96, 1.0, v96
	v_rcp_f32_e32 v200, v96
	v_add_f32_e32 v96, v145, v99
	v_mul_f32_e32 v96, 0xbfb8aa3b, v96
	v_exp_f32_e32 v96, v96
	v_add_f32_e32 v99, v141, v195
	v_lshlrev_b32_e32 v196, 16, v222
	v_add_f32_e32 v193, v136, v196
	v_add_f32_e32 v96, 1.0, v96
	v_rcp_f32_e32 v195, v96
	v_add_f32_e32 v96, v133, v197
	v_mul_f32_e32 v96, 0xbfb8aa3b, v96
	v_exp_f32_e32 v96, v96
	v_lshlrev_b32_e32 v207, 16, v217
	v_and_b32_e32 v201, 0xffff0000, v222
	v_mul_f32_e32 v193, 0xbfb8aa3b, v193
	v_mul_f32_e32 v99, 0xbfb8aa3b, v99
	v_add_f32_e32 v96, 1.0, v96
	v_exp_f32_e32 v196, v193
	v_exp_f32_e32 v193, v99
	v_add_f32_e32 v99, v137, v201
	v_rcp_f32_e32 v201, v96
	v_add_f32_e32 v96, v146, v207
	v_mul_f32_e32 v96, 0xbfb8aa3b, v96
	v_exp_f32_e32 v96, v96
	v_lshlrev_b32_e32 v211, 16, v219
	v_and_b32_e32 v209, 0xffff0000, v217
	v_and_b32_e32 v213, 0xffff0000, v219
	v_add_f32_e32 v96, 1.0, v96
	v_rcp_f32_e32 v210, v96
	v_add_f32_e32 v96, v134, v211
	v_mul_f32_e32 v96, 0xbfb8aa3b, v96
	v_exp_f32_e32 v96, v96
	v_lshlrev_b32_e32 v208, 16, v221
	v_mul_f32_e32 v99, 0xbfb8aa3b, v99
	v_exp_f32_e32 v197, v99
	v_add_f32_e32 v96, 1.0, v96
	v_rcp_f32_e32 v214, v96
	v_add_f32_e32 v96, v147, v209
	v_mul_f32_e32 v96, 0xbfb8aa3b, v96
	v_exp_f32_e32 v96, v96
	v_add_f32_e32 v99, v142, v208
	v_lshlrev_b32_e32 v212, 16, v223
	v_mul_f32_e32 v99, 0xbfb8aa3b, v99
	v_add_f32_e32 v96, 1.0, v96
	v_rcp_f32_e32 v211, v96
	v_add_f32_e32 v96, v135, v213
	v_mul_f32_e32 v96, 0xbfb8aa3b, v96
	v_exp_f32_e32 v96, v96
	v_exp_f32_e32 v208, v99
	v_add_f32_e32 v99, v138, v212
	v_lshlrev_b32_e32 v192, 16, v220
	v_and_b32_e32 v215, 0xffff0000, v221
	v_mul_f32_e32 v99, 0xbfb8aa3b, v99
	v_add_f32_e32 v192, v140, v192
	v_exp_f32_e32 v212, v99
	v_add_f32_e32 v99, v143, v215
	v_mul_f32_e32 v192, 0xbfb8aa3b, v192
	v_mul_f32_e32 v99, 0xbfb8aa3b, v99
	v_add_f32_e32 v96, 1.0, v96
	v_exp_f32_e32 v192, v192
	v_exp_f32_e32 v209, v99
	v_rcp_f32_e32 v215, v96
	s_waitcnt vmcnt(3)
	v_lshlrev_b32_e32 v96, 16, v176
	v_add_f32_e32 v96, v160, v96
	v_mul_f32_e32 v96, 0xbfb8aa3b, v96
	v_exp_f32_e32 v96, v96
	v_and_b32_e32 v216, 0xffff0000, v223
	v_pk_add_f32 v[208:209], v[208:209], 1.0 op_sel_hi:[1,0]
	v_pk_add_f32 v[192:193], v[192:193], 1.0 op_sel_hi:[1,0]
	v_add_f32_e32 v99, v139, v216
	v_pk_mul_f32 v[192:193], v[192:193], v[194:195]
	v_pk_mul_f32 v[194:195], v[208:209], v[210:211]
	v_mul_f32_e32 v99, 0xbfb8aa3b, v99
	v_pk_mul_f32 v[30:31], v[30:31], v[194:195]
	v_pk_add_f32 v[194:195], v[196:197], 1.0 op_sel_hi:[1,0]
	v_exp_f32_e32 v213, v99
	v_pk_mul_f32 v[194:195], v[194:195], v[200:201]
	v_and_b32_e32 v99, 0xffff0000, v176
	v_lshlrev_b32_e32 v176, 16, v178
	v_add_f32_e32 v96, 1.0, v96
	v_pk_mul_f32 v[24:25], v[24:25], v[194:195]
	s_waitcnt vmcnt(1)
	v_lshlrev_b32_e32 v194, 16, v173
	v_and_b32_e32 v201, 0xffff0000, v173
	v_lshlrev_b32_e32 v173, 16, v174
	v_and_b32_e32 v196, 0xffff0000, v174
	v_rcp_f32_e32 v174, v96
	v_add_f32_e32 v96, v152, v176
	v_mul_f32_e32 v96, 0xbfb8aa3b, v96
	v_exp_f32_e32 v96, v96
	v_pk_mul_f32 v[28:29], v[28:29], v[192:193]
	v_pk_add_f32 v[192:193], v[212:213], 1.0 op_sel_hi:[1,0]
	v_lshlrev_b32_e32 v195, 16, v179
	v_pk_mul_f32 v[192:193], v[192:193], v[214:215]
	v_add_f32_e32 v96, 1.0, v96
	v_pk_mul_f32 v[26:27], v[26:27], v[192:193]
	v_lshlrev_b32_e32 v192, 16, v177
	v_and_b32_e32 v193, 0xffff0000, v177
	v_and_b32_e32 v177, 0xffff0000, v178
	v_lshlrev_b32_e32 v178, 16, v172
	v_and_b32_e32 v197, 0xffff0000, v179
	v_and_b32_e32 v179, 0xffff0000, v172
	v_add_f32_e32 v172, v156, v178
	v_rcp_f32_e32 v178, v96
	v_add_f32_e32 v96, v161, v99
	v_mul_f32_e32 v96, 0xbfb8aa3b, v96
	v_exp_f32_e32 v96, v96
	v_lshlrev_b32_e32 v200, 16, v175
	v_and_b32_e32 v207, 0xffff0000, v175
	v_add_f32_e32 v99, v157, v179
	v_add_f32_e32 v96, 1.0, v96
	v_rcp_f32_e32 v175, v96
	v_add_f32_e32 v96, v153, v177
	v_mul_f32_e32 v96, 0xbfb8aa3b, v96
	v_exp_f32_e32 v96, v96
	v_add_f32_e32 v173, v148, v173
	v_mul_f32_e32 v173, 0xbfb8aa3b, v173
	v_mul_f32_e32 v99, 0xbfb8aa3b, v99
	v_add_f32_e32 v96, 1.0, v96
	v_rcp_f32_e32 v179, v96
	v_add_f32_e32 v96, v162, v192
	v_mul_f32_e32 v96, 0xbfb8aa3b, v96
	v_exp_f32_e32 v96, v96
	v_exp_f32_e32 v176, v173
	v_exp_f32_e32 v173, v99
	v_add_f32_e32 v99, v149, v196
	v_mul_f32_e32 v99, 0xbfb8aa3b, v99
	v_add_f32_e32 v96, 1.0, v96
	v_exp_f32_e32 v177, v99
	v_add_f32_e32 v99, v158, v194
	v_rcp_f32_e32 v194, v96
	v_add_f32_e32 v96, v154, v195
	v_mul_f32_e32 v96, 0xbfb8aa3b, v96
	v_exp_f32_e32 v96, v96
	v_mul_f32_e32 v99, 0xbfb8aa3b, v99
	v_exp_f32_e32 v192, v99
	v_add_f32_e32 v99, v150, v200
	v_add_f32_e32 v96, 1.0, v96
	v_rcp_f32_e32 v200, v96
	v_add_f32_e32 v96, v163, v193
	v_mul_f32_e32 v96, 0xbfb8aa3b, v96
	v_exp_f32_e32 v96, v96
	v_mul_f32_e32 v99, 0xbfb8aa3b, v99
	v_exp_f32_e32 v196, v99
	v_add_f32_e32 v99, v159, v201
	v_mul_f32_e32 v172, 0xbfb8aa3b, v172
	v_mul_f32_e32 v99, 0xbfb8aa3b, v99
	v_exp_f32_e32 v172, v172
	v_exp_f32_e32 v193, v99
	v_add_f32_e32 v96, 1.0, v96
	v_rcp_f32_e32 v195, v96
	v_pk_add_f32 v[172:173], v[172:173], 1.0 op_sel_hi:[1,0]
	v_pk_add_f32 v[192:193], v[192:193], 1.0 op_sel_hi:[1,0]
	v_pk_mul_f32 v[172:173], v[172:173], v[174:175]
	v_pk_mul_f32 v[174:175], v[192:193], v[194:195]
	s_waitcnt vmcnt(0)
	v_and_b32_e32 v193, 0xffff0000, v165
	v_pk_mul_f32 v[54:55], v[54:55], v[174:175]
	v_pk_add_f32 v[174:175], v[176:177], 1.0 op_sel_hi:[1,0]
	v_lshlrev_b32_e32 v176, 16, v165
	v_pk_mul_f32 v[174:175], v[174:175], v[178:179]
	v_lshlrev_b32_e32 v165, 16, v166
	v_and_b32_e32 v178, 0xffff0000, v166
	v_add_u32_e32 v166, 0xa0, v98
	v_lshlrev_b32_e32 v192, 16, v167
	v_and_b32_e32 v194, 0xffff0000, v167
	v_mad_i64_i32 v[166:167], s[6:7], v166, s2, v[202:203]
	global_load_dwordx4 v[208:211], v[166:167], off
	global_load_dwordx4 v[212:215], v[166:167], off offset:2048
	v_add_f32_e32 v96, v155, v197
	v_mul_f32_e32 v96, 0xbfb8aa3b, v96
	v_exp_f32_e32 v96, v96
	v_add_f32_e32 v99, v151, v207
	v_mul_f32_e32 v99, 0xbfb8aa3b, v99
	v_exp_f32_e32 v197, v99
	v_add_f32_e32 v96, 1.0, v96
	v_rcp_f32_e32 v201, v96
	v_lshlrev_b32_e32 v96, 16, v168
	v_add_f32_e32 v96, v144, v96
	v_mul_f32_e32 v96, 0xbfb8aa3b, v96
	v_exp_f32_e32 v96, v96
	v_pk_mul_f32 v[48:49], v[48:49], v[174:175]
	v_and_b32_e32 v99, 0xffff0000, v168
	v_lshlrev_b32_e32 v174, 16, v169
	v_and_b32_e32 v175, 0xffff0000, v169
	v_lshlrev_b32_e32 v169, 16, v170
	v_lshlrev_b32_e32 v168, 16, v164
	v_add_f32_e32 v96, 1.0, v96
	v_lshlrev_b32_e32 v177, 16, v171
	v_and_b32_e32 v179, 0xffff0000, v171
	v_and_b32_e32 v171, 0xffff0000, v164
	v_add_f32_e32 v164, v140, v168
	v_rcp_f32_e32 v168, v96
	v_add_f32_e32 v96, v136, v165
	v_add_f32_e32 v165, v132, v169
	v_mul_f32_e32 v165, 0xbfb8aa3b, v165
	v_exp_f32_e32 v165, v165
	v_pk_mul_f32 v[52:53], v[52:53], v[172:173]
	v_pk_add_f32 v[172:173], v[196:197], 1.0 op_sel_hi:[1,0]
	v_mul_f32_e32 v96, 0xbfb8aa3b, v96
	v_pk_mul_f32 v[172:173], v[172:173], v[200:201]
	global_load_dwordx4 v[216:219], v[166:167], off offset:256
	global_load_dwordx4 v[220:223], v[166:167], off offset:2304
	v_pk_mul_f32 v[50:51], v[50:51], v[172:173]
	v_and_b32_e32 v173, 0xffff0000, v170
	v_exp_f32_e32 v170, v96
	v_add_f32_e32 v96, 1.0, v165
	v_rcp_f32_e32 v172, v96
	v_add_f32_e32 v96, v145, v99
	v_mul_f32_e32 v96, 0xbfb8aa3b, v96
	v_exp_f32_e32 v96, v96
	v_add_f32_e32 v99, v141, v171
	v_mul_f32_e32 v99, 0xbfb8aa3b, v99
	v_exp_f32_e32 v165, v99
	v_add_f32_e32 v96, 1.0, v96
	v_rcp_f32_e32 v169, v96
	v_add_f32_e32 v96, v133, v173
	v_mul_f32_e32 v96, 0xbfb8aa3b, v96
	v_exp_f32_e32 v96, v96
	v_add_f32_e32 v99, v137, v178
	v_mul_f32_e32 v99, 0xbfb8aa3b, v99
	v_exp_f32_e32 v171, v99
	v_add_f32_e32 v96, 1.0, v96
	v_rcp_f32_e32 v173, v96
	v_add_f32_e32 v96, v146, v174
	v_mul_f32_e32 v96, 0xbfb8aa3b, v96
	v_exp_f32_e32 v96, v96
	v_add_f32_e32 v99, v142, v176
	v_mul_f32_e32 v99, 0xbfb8aa3b, v99
	v_exp_f32_e32 v174, v99
	v_add_f32_e32 v96, 1.0, v96
	v_rcp_f32_e32 v176, v96
	v_add_f32_e32 v96, v134, v177
	v_mul_f32_e32 v96, 0xbfb8aa3b, v96
	v_exp_f32_e32 v96, v96
	v_add_f32_e32 v99, v138, v192
	v_mul_f32_e32 v99, 0xbfb8aa3b, v99
	v_exp_f32_e32 v178, v99
	v_add_f32_e32 v96, 1.0, v96
	v_rcp_f32_e32 v192, v96
	v_add_f32_e32 v96, v147, v175
	v_mul_f32_e32 v96, 0xbfb8aa3b, v96
	v_exp_f32_e32 v96, v96
	v_add_f32_e32 v99, v143, v193
	v_mul_f32_e32 v99, 0xbfb8aa3b, v99
	v_exp_f32_e32 v175, v99
	v_add_f32_e32 v96, 1.0, v96
	v_rcp_f32_e32 v177, v96
	v_add_f32_e32 v96, v135, v179
	v_mul_f32_e32 v96, 0xbfb8aa3b, v96
	v_exp_f32_e32 v96, v96
	v_add_f32_e32 v99, v139, v194
	v_mul_f32_e32 v164, 0xbfb8aa3b, v164
	v_mul_f32_e32 v99, 0xbfb8aa3b, v99
	v_add_f32_e32 v96, 1.0, v96
	v_rcp_f32_e32 v193, v96
	v_add_u32_e32 v96, 0xb0, v98
	v_exp_f32_e32 v164, v164
	v_exp_f32_e32 v179, v99
	v_mad_i64_i32 v[98:99], s[6:7], v96, s2, v[202:203]
	s_waitcnt vmcnt(3)
	v_lshlrev_b32_e32 v96, 16, v208
	v_add_f32_e32 v96, v160, v96
	v_mul_f32_e32 v96, 0xbfb8aa3b, v96
	v_exp_f32_e32 v96, v96
	v_pk_add_f32 v[164:165], v[164:165], 1.0 op_sel_hi:[1,0]
	v_pk_add_f32 v[174:175], v[174:175], 1.0 op_sel_hi:[1,0]
	v_pk_mul_f32 v[164:165], v[164:165], v[168:169]
	v_add_f32_e32 v96, 1.0, v96
	v_pk_mul_f32 v[20:21], v[20:21], v[164:165]
	v_pk_add_f32 v[164:165], v[178:179], 1.0 op_sel_hi:[1,0]
	v_pk_mul_f32 v[168:169], v[174:175], v[176:177]
	v_pk_mul_f32 v[164:165], v[164:165], v[192:193]
	v_lshlrev_b32_e32 v193, 16, v210
	v_rcp_f32_e32 v192, v96
	v_add_f32_e32 v96, v152, v193
	v_mul_f32_e32 v96, 0xbfb8aa3b, v96
	v_exp_f32_e32 v96, v96
	v_pk_mul_f32 v[22:23], v[22:23], v[168:169]
	v_pk_add_f32 v[168:169], v[170:171], 1.0 op_sel_hi:[1,0]
	v_pk_mul_f32 v[18:19], v[18:19], v[164:165]
	v_pk_mul_f32 v[168:169], v[168:169], v[172:173]
	v_add_f32_e32 v96, 1.0, v96
	v_pk_mul_f32 v[16:17], v[16:17], v[168:169]
	global_load_dwordx4 v[176:179], v[98:99], off
	global_load_dwordx4 v[168:171], v[98:99], off offset:256
	global_load_dwordx4 v[172:175], v[98:99], off offset:2048
	global_load_dwordx4 v[164:167], v[98:99], off offset:2304
	v_and_b32_e32 v99, 0xffff0000, v208
	v_rcp_f32_e32 v196, v96
	v_add_f32_e32 v96, v161, v99
	v_mul_f32_e32 v96, 0xbfb8aa3b, v96
	v_exp_f32_e32 v96, v96
	s_waitcnt vmcnt(6)
	v_lshlrev_b32_e32 v194, 16, v214
	v_add_f32_e32 v193, v148, v194
	v_and_b32_e32 v195, 0xffff0000, v210
	v_mul_f32_e32 v193, 0xbfb8aa3b, v193
	v_add_f32_e32 v96, 1.0, v96
	v_exp_f32_e32 v194, v193
	v_rcp_f32_e32 v193, v96
	v_add_f32_e32 v96, v153, v195
	v_mul_f32_e32 v96, 0xbfb8aa3b, v96
	v_exp_f32_e32 v96, v96
	v_lshlrev_b32_e32 v200, 16, v209
	v_and_b32_e32 v197, 0xffff0000, v212
	v_add_f32_e32 v99, v157, v197
	v_add_f32_e32 v96, 1.0, v96
	v_rcp_f32_e32 v197, v96
	v_add_f32_e32 v96, v162, v200
	v_mul_f32_e32 v96, 0xbfb8aa3b, v96
	v_exp_f32_e32 v96, v96
	v_lshlrev_b32_e32 v203, 16, v211
	v_lshlrev_b32_e32 v202, 16, v213
	v_add_f32_e32 v200, v158, v202
	v_add_f32_e32 v96, 1.0, v96
	v_rcp_f32_e32 v202, v96
	v_add_f32_e32 v96, v154, v203
	v_mul_f32_e32 v96, 0xbfb8aa3b, v96
	v_exp_f32_e32 v96, v96
	v_and_b32_e32 v201, 0xffff0000, v209
	v_lshlrev_b32_e32 v210, 16, v215
	v_add_f32_e32 v203, v150, v210
	v_add_f32_e32 v96, 1.0, v96
	v_rcp_f32_e32 v210, v96
	v_add_f32_e32 v96, v163, v201
	v_mul_f32_e32 v96, 0xbfb8aa3b, v96
	v_exp_f32_e32 v96, v96
	v_and_b32_e32 v207, 0xffff0000, v211
	v_and_b32_e32 v208, 0xffff0000, v214
	v_mul_f32_e32 v203, 0xbfb8aa3b, v203
	v_add_f32_e32 v96, 1.0, v96
	v_add_f32_e32 v195, v149, v208
	v_exp_f32_e32 v208, v203
	v_rcp_f32_e32 v203, v96
	v_add_f32_e32 v96, v155, v207
	v_mul_f32_e32 v96, 0xbfb8aa3b, v96
	v_exp_f32_e32 v96, v96
	v_lshlrev_b32_e32 v98, 16, v212
	v_and_b32_e32 v209, 0xffff0000, v213
	v_add_f32_e32 v98, v156, v98
	v_add_f32_e32 v201, v159, v209
	v_mul_f32_e32 v98, 0xbfb8aa3b, v98
	v_mul_f32_e32 v99, 0xbfb8aa3b, v99
	v_mul_f32_e32 v200, 0xbfb8aa3b, v200
	v_mul_f32_e32 v201, 0xbfb8aa3b, v201
	v_and_b32_e32 v211, 0xffff0000, v215
	v_exp_f32_e32 v98, v98
	v_exp_f32_e32 v99, v99
	v_exp_f32_e32 v200, v200
	v_exp_f32_e32 v201, v201
	v_add_f32_e32 v96, 1.0, v96
	v_mul_f32_e32 v195, 0xbfb8aa3b, v195
	v_add_f32_e32 v207, v151, v211
	v_rcp_f32_e32 v211, v96
	s_waitcnt vmcnt(5)
	v_lshlrev_b32_e32 v96, 16, v216
	v_exp_f32_e32 v195, v195
	v_add_f32_e32 v96, v144, v96
	v_mul_f32_e32 v96, 0xbfb8aa3b, v96
	v_pk_add_f32 v[200:201], v[200:201], 1.0 op_sel_hi:[1,0]
	v_pk_add_f32 v[98:99], v[98:99], 1.0 op_sel_hi:[1,0]
	v_exp_f32_e32 v96, v96
	v_pk_mul_f32 v[98:99], v[98:99], v[192:193]
	v_pk_mul_f32 v[192:193], v[200:201], v[202:203]
	v_mul_f32_e32 v207, 0xbfb8aa3b, v207
	v_pk_mul_f32 v[46:47], v[46:47], v[192:193]
	v_pk_add_f32 v[192:193], v[194:195], 1.0 op_sel_hi:[1,0]
	v_add_f32_e32 v96, 1.0, v96
	v_pk_mul_f32 v[192:193], v[192:193], v[196:197]
	v_exp_f32_e32 v209, v207
	v_pk_mul_f32 v[40:41], v[40:41], v[192:193]
	v_lshlrev_b32_e32 v193, 16, v218
	v_rcp_f32_e32 v192, v96
	v_add_f32_e32 v96, v132, v193
	v_mul_f32_e32 v96, 0xbfb8aa3b, v96
	v_exp_f32_e32 v96, v96
	v_pk_mul_f32 v[44:45], v[44:45], v[98:99]
	v_pk_add_f32 v[98:99], v[208:209], 1.0 op_sel_hi:[1,0]
	s_waitcnt vmcnt(4)
	v_lshlrev_b32_e32 v194, 16, v222
	v_pk_mul_f32 v[98:99], v[98:99], v[210:211]
	v_add_f32_e32 v96, 1.0, v96
	v_pk_mul_f32 v[42:43], v[42:43], v[98:99]
	v_and_b32_e32 v99, 0xffff0000, v216
	v_rcp_f32_e32 v196, v96
	v_add_f32_e32 v96, v145, v99
	v_mul_f32_e32 v96, 0xbfb8aa3b, v96
	v_exp_f32_e32 v96, v96
	v_add_f32_e32 v193, v136, v194
	v_and_b32_e32 v195, 0xffff0000, v218
	v_mul_f32_e32 v193, 0xbfb8aa3b, v193
	v_add_f32_e32 v96, 1.0, v96
	v_exp_f32_e32 v194, v193
	v_rcp_f32_e32 v193, v96
	v_add_f32_e32 v96, v133, v195
	v_mul_f32_e32 v96, 0xbfb8aa3b, v96
	v_exp_f32_e32 v96, v96
	v_lshlrev_b32_e32 v200, 16, v217
	v_and_b32_e32 v197, 0xffff0000, v220
	v_add_f32_e32 v99, v141, v197
	v_add_f32_e32 v96, 1.0, v96
	v_rcp_f32_e32 v197, v96
	v_add_f32_e32 v96, v146, v200
	v_mul_f32_e32 v96, 0xbfb8aa3b, v96
	v_exp_f32_e32 v96, v96
	v_lshlrev_b32_e32 v203, 16, v219
	v_lshlrev_b32_e32 v202, 16, v221
	v_add_f32_e32 v200, v142, v202
	v_add_f32_e32 v96, 1.0, v96
	v_rcp_f32_e32 v202, v96
	v_add_f32_e32 v96, v134, v203
	v_mul_f32_e32 v96, 0xbfb8aa3b, v96
	v_exp_f32_e32 v96, v96
	v_and_b32_e32 v201, 0xffff0000, v217
	v_lshlrev_b32_e32 v210, 16, v223
	v_add_f32_e32 v203, v138, v210
	v_add_f32_e32 v96, 1.0, v96
	v_rcp_f32_e32 v210, v96
	v_add_f32_e32 v96, v147, v201
	v_mul_f32_e32 v96, 0xbfb8aa3b, v96
	v_exp_f32_e32 v96, v96
	v_and_b32_e32 v207, 0xffff0000, v219
	v_and_b32_e32 v208, 0xffff0000, v222
	v_mul_f32_e32 v203, 0xbfb8aa3b, v203
	v_add_f32_e32 v96, 1.0, v96
	v_add_f32_e32 v195, v137, v208
	v_exp_f32_e32 v208, v203
	v_rcp_f32_e32 v203, v96
	v_add_f32_e32 v96, v135, v207
	v_mul_f32_e32 v96, 0xbfb8aa3b, v96
	v_exp_f32_e32 v96, v96
	v_lshlrev_b32_e32 v98, 16, v220
	v_and_b32_e32 v209, 0xffff0000, v221
	v_add_f32_e32 v98, v140, v98
	v_add_f32_e32 v201, v143, v209
	v_and_b32_e32 v211, 0xffff0000, v223
	v_mul_f32_e32 v98, 0xbfb8aa3b, v98
	v_mul_f32_e32 v99, 0xbfb8aa3b, v99
	v_mul_f32_e32 v200, 0xbfb8aa3b, v200
	v_mul_f32_e32 v201, 0xbfb8aa3b, v201
	v_exp_f32_e32 v98, v98
	v_exp_f32_e32 v99, v99
	v_exp_f32_e32 v200, v200
	v_exp_f32_e32 v201, v201
	v_add_f32_e32 v207, v139, v211
	v_add_f32_e32 v96, 1.0, v96
	v_mul_f32_e32 v195, 0xbfb8aa3b, v195
	v_mul_f32_e32 v207, 0xbfb8aa3b, v207
	v_rcp_f32_e32 v211, v96
	s_waitcnt vmcnt(3)
	v_lshlrev_b32_e32 v96, 16, v176
	v_exp_f32_e32 v195, v195
	v_exp_f32_e32 v209, v207
	v_add_f32_e32 v96, v160, v96
	v_mul_f32_e32 v96, 0xbfb8aa3b, v96
	v_pk_add_f32 v[200:201], v[200:201], 1.0 op_sel_hi:[1,0]
	v_pk_add_f32 v[98:99], v[98:99], 1.0 op_sel_hi:[1,0]
	v_exp_f32_e32 v96, v96
	v_pk_mul_f32 v[98:99], v[98:99], v[192:193]
	v_pk_mul_f32 v[192:193], v[200:201], v[202:203]
	v_pk_mul_f32 v[12:13], v[12:13], v[98:99]
	v_pk_mul_f32 v[14:15], v[14:15], v[192:193]
	v_pk_add_f32 v[98:99], v[208:209], 1.0 op_sel_hi:[1,0]
	v_pk_add_f32 v[192:193], v[194:195], 1.0 op_sel_hi:[1,0]
	v_pk_mul_f32 v[98:99], v[98:99], v[210:211]
	v_pk_mul_f32 v[192:193], v[192:193], v[196:197]
	v_pk_mul_f32 v[10:11], v[10:11], v[98:99]
	v_pk_mul_f32 v[8:9], v[8:9], v[192:193]
	v_lshlrev_b32_e32 v192, 16, v178
	s_waitcnt vmcnt(1)
	v_lshlrev_b32_e32 v98, 16, v172
	v_add_f32_e32 v96, 1.0, v96
	v_add_f32_e32 v98, v156, v98
	v_rcp_f32_e32 v156, v96
	v_add_f32_e32 v96, v152, v192
	v_mul_f32_e32 v96, 0xbfb8aa3b, v96
	v_exp_f32_e32 v96, v96
	v_and_b32_e32 v99, 0xffff0000, v176
	v_and_b32_e32 v178, 0xffff0000, v178
	v_and_b32_e32 v172, 0xffff0000, v172
	v_add_f32_e32 v96, 1.0, v96
	v_rcp_f32_e32 v152, v96
	v_add_f32_e32 v96, v161, v99
	v_mul_f32_e32 v96, 0xbfb8aa3b, v96
	v_exp_f32_e32 v96, v96
	v_add_f32_e32 v99, v157, v172
	v_lshlrev_b32_e32 v176, 16, v177
	v_lshlrev_b32_e32 v193, 16, v179
	v_add_f32_e32 v96, 1.0, v96
	v_rcp_f32_e32 v157, v96
	v_add_f32_e32 v96, v153, v178
	v_mul_f32_e32 v96, 0xbfb8aa3b, v96
	v_exp_f32_e32 v96, v96
	v_and_b32_e32 v177, 0xffff0000, v177
	v_and_b32_e32 v179, 0xffff0000, v179
	v_lshlrev_b32_e32 v196, 16, v175
	v_add_f32_e32 v96, 1.0, v96
	v_rcp_f32_e32 v153, v96
	v_add_f32_e32 v96, v162, v176
	v_mul_f32_e32 v96, 0xbfb8aa3b, v96
	v_exp_f32_e32 v96, v96
	v_and_b32_e32 v175, 0xffff0000, v175
	v_mul_f32_e32 v98, 0xbfb8aa3b, v98
	v_mul_f32_e32 v99, 0xbfb8aa3b, v99
	v_add_f32_e32 v96, 1.0, v96
	v_rcp_f32_e32 v160, v96
	v_add_f32_e32 v96, v154, v193
	v_mul_f32_e32 v96, 0xbfb8aa3b, v96
	v_exp_f32_e32 v96, v96
	v_exp_f32_e32 v98, v98
	v_exp_f32_e32 v99, v99
	v_add_f32_e32 v150, v150, v196
	v_add_f32_e32 v96, 1.0, v96
	v_rcp_f32_e32 v154, v96
	v_add_f32_e32 v96, v163, v177
	v_mul_f32_e32 v96, 0xbfb8aa3b, v96
	v_exp_f32_e32 v96, v96
	v_add_f32_e32 v151, v151, v175
	v_mul_f32_e32 v150, 0xbfb8aa3b, v150
	v_mul_f32_e32 v151, 0xbfb8aa3b, v151
	v_add_f32_e32 v96, 1.0, v96
	v_rcp_f32_e32 v161, v96
	v_add_f32_e32 v96, v155, v179
	v_mul_f32_e32 v96, 0xbfb8aa3b, v96
	v_exp_f32_e32 v96, v96
	v_exp_f32_e32 v150, v150
	v_exp_f32_e32 v151, v151
	v_pk_add_f32 v[98:99], v[98:99], 1.0 op_sel_hi:[1,0]
	v_add_f32_e32 v96, 1.0, v96
	v_rcp_f32_e32 v155, v96
	v_lshlrev_b32_e32 v96, 16, v168
	v_add_f32_e32 v96, v144, v96
	v_mul_f32_e32 v96, 0xbfb8aa3b, v96
	v_exp_f32_e32 v96, v96
	v_pk_mul_f32 v[98:99], v[98:99], v[156:157]
	v_lshlrev_b32_e32 v194, 16, v173
	v_and_b32_e32 v173, 0xffff0000, v173
	v_pk_mul_f32 v[36:37], v[36:37], v[98:99]
	v_pk_add_f32 v[98:99], v[150:151], 1.0 op_sel_hi:[1,0]
	v_add_f32_e32 v158, v158, v194
	v_add_f32_e32 v159, v159, v173
	v_pk_mul_f32 v[98:99], v[98:99], v[154:155]
	v_mul_f32_e32 v158, 0xbfb8aa3b, v158
	v_mul_f32_e32 v159, 0xbfb8aa3b, v159
	v_pk_mul_f32 v[34:35], v[34:35], v[98:99]
	v_lshlrev_b32_e32 v150, 16, v170
	s_waitcnt vmcnt(0)
	v_lshlrev_b32_e32 v98, 16, v164
	v_add_f32_e32 v96, 1.0, v96
	v_exp_f32_e32 v158, v158
	v_exp_f32_e32 v159, v159
	v_add_f32_e32 v98, v140, v98
	v_rcp_f32_e32 v140, v96
	v_add_f32_e32 v96, v132, v150
	v_mul_f32_e32 v96, 0xbfb8aa3b, v96
	v_exp_f32_e32 v96, v96
	v_pk_add_f32 v[158:159], v[158:159], 1.0 op_sel_hi:[1,0]
	v_and_b32_e32 v99, 0xffff0000, v168
	v_pk_mul_f32 v[156:157], v[158:159], v[160:161]
	v_add_f32_e32 v96, 1.0, v96
	v_pk_mul_f32 v[38:39], v[38:39], v[156:157]
	v_lshlrev_b32_e32 v157, 16, v166
	v_add_f32_e32 v132, v136, v157
	v_rcp_f32_e32 v136, v96
	v_add_f32_e32 v96, v145, v99
	v_mul_f32_e32 v96, 0xbfb8aa3b, v96
	v_exp_f32_e32 v96, v96
	v_lshlrev_b32_e32 v195, 16, v174
	v_and_b32_e32 v174, 0xffff0000, v174
	v_add_f32_e32 v148, v148, v195
	v_add_f32_e32 v149, v149, v174
	v_mul_f32_e32 v148, 0xbfb8aa3b, v148
	v_mul_f32_e32 v149, 0xbfb8aa3b, v149
	v_and_b32_e32 v151, 0xffff0000, v170
	v_and_b32_e32 v154, 0xffff0000, v164
	v_add_f32_e32 v96, 1.0, v96
	v_exp_f32_e32 v148, v148
	v_exp_f32_e32 v149, v149
	v_add_f32_e32 v99, v141, v154
	v_rcp_f32_e32 v141, v96
	v_add_f32_e32 v96, v133, v151
	v_mul_f32_e32 v96, 0xbfb8aa3b, v96
	v_exp_f32_e32 v96, v96
	v_pk_add_f32 v[148:149], v[148:149], 1.0 op_sel_hi:[1,0]
	v_and_b32_e32 v158, 0xffff0000, v166
	v_pk_mul_f32 v[148:149], v[148:149], v[152:153]
	v_add_f32_e32 v96, 1.0, v96
	v_pk_mul_f32 v[32:33], v[32:33], v[148:149]
	v_lshlrev_b32_e32 v148, 16, v169
	v_add_f32_e32 v133, v137, v158
	v_rcp_f32_e32 v137, v96
	v_add_f32_e32 v96, v146, v148
	v_mul_f32_e32 v96, 0xbfb8aa3b, v96
	v_exp_f32_e32 v96, v96
	v_lshlrev_b32_e32 v152, 16, v171
	v_and_b32_e32 v149, 0xffff0000, v169
	v_lshlrev_b32_e32 v159, 16, v167
	v_add_f32_e32 v96, 1.0, v96
	v_rcp_f32_e32 v144, v96
	v_add_f32_e32 v96, v134, v152
	v_mul_f32_e32 v96, 0xbfb8aa3b, v96
	v_exp_f32_e32 v96, v96
	v_add_f32_e32 v134, v138, v159
	v_and_b32_e32 v153, 0xffff0000, v171
	v_lshlrev_b32_e32 v155, 16, v165
	v_add_f32_e32 v96, 1.0, v96
	v_rcp_f32_e32 v138, v96
	v_add_f32_e32 v96, v147, v149
	v_mul_f32_e32 v96, 0xbfb8aa3b, v96
	v_exp_f32_e32 v96, v96
	v_and_b32_e32 v156, 0xffff0000, v165
	v_and_b32_e32 v160, 0xffff0000, v167
	v_mul_f32_e32 v98, 0xbfb8aa3b, v98
	v_add_f32_e32 v96, 1.0, v96
	v_rcp_f32_e32 v145, v96
	v_add_f32_e32 v96, v135, v153
	v_mul_f32_e32 v96, 0xbfb8aa3b, v96
	v_exp_f32_e32 v96, v96
	v_mul_f32_e32 v99, 0xbfb8aa3b, v99
	v_exp_f32_e32 v98, v98
	v_exp_f32_e32 v99, v99
	v_add_f32_e32 v142, v142, v155
	v_add_f32_e32 v143, v143, v156
	v_add_f32_e32 v135, v139, v160
	v_mul_f32_e32 v132, 0xbfb8aa3b, v132
	v_mul_f32_e32 v133, 0xbfb8aa3b, v133
	v_mul_f32_e32 v142, 0xbfb8aa3b, v142
	v_mul_f32_e32 v134, 0xbfb8aa3b, v134
	v_mul_f32_e32 v143, 0xbfb8aa3b, v143
	v_mul_f32_e32 v135, 0xbfb8aa3b, v135
	v_exp_f32_e32 v132, v132
	v_exp_f32_e32 v133, v133
	v_exp_f32_e32 v142, v142
	v_exp_f32_e32 v134, v134
	v_exp_f32_e32 v143, v143
	v_exp_f32_e32 v135, v135
	v_add_f32_e32 v96, 1.0, v96
	v_rcp_f32_e32 v139, v96
	v_pk_add_f32 v[98:99], v[98:99], 1.0 op_sel_hi:[1,0]
	v_pk_add_f32 v[142:143], v[142:143], 1.0 op_sel_hi:[1,0]
	v_pk_mul_f32 v[98:99], v[98:99], v[140:141]
	v_pk_add_f32 v[132:133], v[132:133], 1.0 op_sel_hi:[1,0]
	v_pk_mul_f32 v[4:5], v[4:5], v[98:99]
	v_pk_add_f32 v[98:99], v[134:135], 1.0 op_sel_hi:[1,0]
	v_pk_mul_f32 v[140:141], v[142:143], v[144:145]
	v_pk_mul_f32 v[132:133], v[132:133], v[136:137]
	v_pk_mul_f32 v[98:99], v[98:99], v[138:139]
	v_pk_mul_f32 v[6:7], v[6:7], v[140:141]
	v_pk_mul_f32 v[2:3], v[2:3], v[98:99]
	v_pk_mul_f32 v[0:1], v[0:1], v[132:133]
	s_andn2_b64 vcc, exec, s[0:1]
	s_mov_b64 s[0:1], -1
	s_cbranch_vccnz .LBB0_270
